# P8 SwiGLU epilogue: plain f32 mul/add steps of adjacent outputs done with packed v_pk_mul_f32/v_pk_add_f32 (same f32 arithmetic per element)
# speedup vs baseline: 1.0239x; 1.0027x over previous
; #define PG8_LAS __attribute__((address_space(3)))
; __device__ __forceinline__ u32x4 pack8(f32x4 v0, f32x4 v1) { u32x4 w; w.x = cvt_pk_bf16(v0[0], v0[1]); w.y = cvt_pk_bf16(v0[2], v0[3]); w.z = cvt_pk_bf16(v1[0], v1[1]); w.w = cvt_pk_bf16(v1[2], v1[3]); return w; }
;     __device__ __forceinline__ void operator()(Acc& acc, const Unit& u, int wr, int wc, int fr, int fq, PG8_LAS unsigned char* xl) const {
;         const PG8_LAS float* S = rs_table(SS, u.r0, xl);
; #pragma unroll
;         for (int ai = 0; ai < 2; ++ai)
; #pragma unroll
;             for (int m = 0; m < 4; ++m) { const int rl = ai * HALF + wr * 64 + m * 16 + fr; const int row = u.r0 + rl; const float s = S[rl], cs = -LOG2E * s, s2 = s * s;
;                 f32x4 o[2];
; #pragma unroll
;                 for (int n = 0; n < 2; ++n) { const f32x4 g = acc[ai][0][m][n], gu = acc[ai][0][m][n] * acc[ai][1][m][n]; f32x4 r;
; #pragma unroll
;                     for (int e = 0; e < 4; ++e) r[e] = gu[e] * (s2 * __builtin_amdgcn_rcpf(1.f + __builtin_amdgcn_exp2f(cs * g[e])));
;                     o[n] = r; }
;                 *(u32x4*)(H + (size_t)row * ldc + (u.c0 >> 1) + wc * 32 + 8 * fq) = pack8(o[0], o[1]); }
.Lrs8_skip:
	ds_read_b32 v184, v148
	ds_read_b32 v185, v150
	ds_read_b32 v186, v152
	ds_read_b32 v187, v155
	ds_read_b32 v188, v157
	ds_read_b32 v189, v159
	ds_read_b32 v190, v161
	ds_read_b32 v191, v163
	s_ashr_i32 s2, s33, 1
	s_ashr_i32 s3, s2, 31
	s_lshl_b64 s[2:3], s[2:3], 1
	s_andn2_b64 vcc, exec, s[6:7]
	v_mov_b64_e32 v[170:171], s[12:13]
	v_mov_b32_e32 v180, 1.0
	v_pk_mul_f32 v[120:121], v[124:125], v[120:121]
	v_pk_mul_f32 v[122:123], v[126:127], v[122:123]
	v_pk_mul_f32 v[112:113], v[116:117], v[112:113]
	v_pk_mul_f32 v[114:115], v[118:119], v[114:115]
	s_waitcnt lgkmcnt(0)
	v_mul_f32_e32 v174, 0xbfb8aa3b, v184
	v_mul_f32_e32 v176, v184, v184
	v_pk_mul_f32 v[124:125], v[124:125], v[174:175] op_sel_hi:[1,0]
	v_pk_mul_f32 v[126:127], v[126:127], v[174:175] op_sel_hi:[1,0]
	v_pk_mul_f32 v[116:117], v[116:117], v[174:175] op_sel_hi:[1,0]
	v_pk_mul_f32 v[118:119], v[118:119], v[174:175] op_sel_hi:[1,0]
	v_exp_f32_e32 v124, v124
	v_exp_f32_e32 v125, v125
	v_exp_f32_e32 v126, v126
	v_exp_f32_e32 v127, v127
	v_exp_f32_e32 v116, v116
	v_exp_f32_e32 v117, v117
	v_exp_f32_e32 v118, v118
	v_exp_f32_e32 v119, v119
	v_pk_add_f32 v[124:125], v[124:125], v[180:181] op_sel_hi:[1,0]
	v_pk_add_f32 v[126:127], v[126:127], v[180:181] op_sel_hi:[1,0]
	v_pk_add_f32 v[116:117], v[116:117], v[180:181] op_sel_hi:[1,0]
	v_pk_add_f32 v[118:119], v[118:119], v[180:181] op_sel_hi:[1,0]
	v_add_u32_e32 v172, s60, v146
	v_rcp_f32_e32 v124, v124
	v_rcp_f32_e32 v125, v125
	v_rcp_f32_e32 v126, v126
	v_rcp_f32_e32 v127, v127
	v_rcp_f32_e32 v116, v116
	v_rcp_f32_e32 v117, v117
	v_rcp_f32_e32 v118, v118
	v_rcp_f32_e32 v119, v119
	v_mad_i64_i32 v[172:173], s[30:31], v172, s64, v[170:171]
	v_lshl_add_u64 v[172:173], v[172:173], 0, s[2:3]
	v_lshl_add_u64 v[172:173], v[172:173], 0, s[8:9]
	v_lshl_add_u64 v[172:173], v[172:173], 0, v[136:137]
	v_pk_mul_f32 v[124:125], v[124:125], v[176:177] op_sel_hi:[1,0]
	v_pk_mul_f32 v[126:127], v[126:127], v[176:177] op_sel_hi:[1,0]
	v_pk_mul_f32 v[116:117], v[116:117], v[176:177] op_sel_hi:[1,0]
	v_pk_mul_f32 v[118:119], v[118:119], v[176:177] op_sel_hi:[1,0]
	v_pk_mul_f32 v[120:121], v[120:121], v[124:125]
	v_pk_mul_f32 v[122:123], v[122:123], v[126:127]
	v_pk_mul_f32 v[112:113], v[112:113], v[116:117]
	v_pk_mul_f32 v[114:115], v[114:115], v[118:119]
	v_cvt_pk_bf16_f32 v124, v120, v121
	v_cvt_pk_bf16_f32 v125, v122, v123
	v_cvt_pk_bf16_f32 v126, v112, v113
	v_cvt_pk_bf16_f32 v127, v114, v115
	flat_store_dwordx4 v[172:173], v[124:127]
	v_pk_mul_f32 v[104:105], v[108:109], v[104:105]
	v_pk_mul_f32 v[106:107], v[110:111], v[106:107]
	v_pk_mul_f32 v[96:97], v[100:101], v[96:97]
	v_pk_mul_f32 v[98:99], v[102:103], v[98:99]
	v_mul_f32_e32 v174, 0xbfb8aa3b, v185
	v_mul_f32_e32 v176, v185, v185
	v_pk_mul_f32 v[108:109], v[108:109], v[174:175] op_sel_hi:[1,0]
	v_pk_mul_f32 v[110:111], v[110:111], v[174:175] op_sel_hi:[1,0]
	v_pk_mul_f32 v[100:101], v[100:101], v[174:175] op_sel_hi:[1,0]
	v_pk_mul_f32 v[102:103], v[102:103], v[174:175] op_sel_hi:[1,0]
	v_exp_f32_e32 v108, v108
	v_exp_f32_e32 v109, v109
	v_exp_f32_e32 v110, v110
	v_exp_f32_e32 v111, v111
	v_exp_f32_e32 v100, v100
	v_exp_f32_e32 v101, v101
	v_exp_f32_e32 v102, v102
	v_exp_f32_e32 v103, v103
	v_pk_add_f32 v[108:109], v[108:109], v[180:181] op_sel_hi:[1,0]
	v_pk_add_f32 v[110:111], v[110:111], v[180:181] op_sel_hi:[1,0]
	v_pk_add_f32 v[100:101], v[100:101], v[180:181] op_sel_hi:[1,0]
	v_pk_add_f32 v[102:103], v[102:103], v[180:181] op_sel_hi:[1,0]
	v_add_u32_e32 v172, s60, v149
	v_rcp_f32_e32 v108, v108
	v_rcp_f32_e32 v109, v109
	v_rcp_f32_e32 v110, v110
	v_rcp_f32_e32 v111, v111
	v_rcp_f32_e32 v100, v100
	v_rcp_f32_e32 v101, v101
	v_rcp_f32_e32 v102, v102
	v_rcp_f32_e32 v103, v103
	v_mad_i64_i32 v[172:173], s[30:31], v172, s64, v[170:171]
	v_lshl_add_u64 v[172:173], v[172:173], 0, s[2:3]
	v_lshl_add_u64 v[172:173], v[172:173], 0, s[8:9]
	v_lshl_add_u64 v[172:173], v[172:173], 0, v[136:137]
	v_pk_mul_f32 v[108:109], v[108:109], v[176:177] op_sel_hi:[1,0]
	v_pk_mul_f32 v[110:111], v[110:111], v[176:177] op_sel_hi:[1,0]
	v_pk_mul_f32 v[100:101], v[100:101], v[176:177] op_sel_hi:[1,0]
	v_pk_mul_f32 v[102:103], v[102:103], v[176:177] op_sel_hi:[1,0]
	v_pk_mul_f32 v[104:105], v[104:105], v[108:109]
	v_pk_mul_f32 v[106:107], v[106:107], v[110:111]
	v_pk_mul_f32 v[96:97], v[96:97], v[100:101]
	v_pk_mul_f32 v[98:99], v[98:99], v[102:103]
	v_cvt_pk_bf16_f32 v108, v104, v105
	v_cvt_pk_bf16_f32 v109, v106, v107
	v_cvt_pk_bf16_f32 v110, v96, v97
	v_cvt_pk_bf16_f32 v111, v98, v99
	flat_store_dwordx4 v[172:173], v[108:111]
	v_pk_mul_f32 v[88:89], v[92:93], v[88:89]
	v_pk_mul_f32 v[90:91], v[94:95], v[90:91]
	v_pk_mul_f32 v[80:81], v[84:85], v[80:81]
	v_pk_mul_f32 v[82:83], v[86:87], v[82:83]
	v_mul_f32_e32 v174, 0xbfb8aa3b, v186
	v_mul_f32_e32 v176, v186, v186
	v_pk_mul_f32 v[92:93], v[92:93], v[174:175] op_sel_hi:[1,0]
	v_pk_mul_f32 v[94:95], v[94:95], v[174:175] op_sel_hi:[1,0]
	v_pk_mul_f32 v[84:85], v[84:85], v[174:175] op_sel_hi:[1,0]
	v_pk_mul_f32 v[86:87], v[86:87], v[174:175] op_sel_hi:[1,0]
	v_exp_f32_e32 v92, v92
	v_exp_f32_e32 v93, v93
	v_exp_f32_e32 v94, v94
	v_exp_f32_e32 v95, v95
	v_exp_f32_e32 v84, v84
	v_exp_f32_e32 v85, v85
	v_exp_f32_e32 v86, v86
	v_exp_f32_e32 v87, v87
	v_pk_add_f32 v[92:93], v[92:93], v[180:181] op_sel_hi:[1,0]
	v_pk_add_f32 v[94:95], v[94:95], v[180:181] op_sel_hi:[1,0]
	v_pk_add_f32 v[84:85], v[84:85], v[180:181] op_sel_hi:[1,0]
	v_pk_add_f32 v[86:87], v[86:87], v[180:181] op_sel_hi:[1,0]
	v_add_u32_e32 v172, s60, v151
	v_rcp_f32_e32 v92, v92
	v_rcp_f32_e32 v93, v93
	v_rcp_f32_e32 v94, v94
	v_rcp_f32_e32 v95, v95
	v_rcp_f32_e32 v84, v84
	v_rcp_f32_e32 v85, v85
; __device__ __forceinline__ u32x4 pack8(f32x4 v0, f32x4 v1) { u32x4 w; w.x = cvt_pk_bf16(v0[0], v0[1]); w.y = cvt_pk_bf16(v0[2], v0[3]); w.z = cvt_pk_bf16(v1[0], v1[1]); w.w = cvt_pk_bf16(v1[2], v1[3]); return w; }
;     __device__ __forceinline__ void operator()(Acc& acc, const Unit& u, int wr, int wc, int fr, int fq, PG8_LAS unsigned char* xl) const {
;     ...
;             for (int m = 0; m < 4; ++m) { const int rl = ai * HALF + wr * 64 + m * 16 + fr; const int row = u.r0 + rl; const float s = S[rl], cs = -LOG2E * s, s2 = s * s;
;                 f32x4 o[2];
; #pragma unroll
;                 for (int n = 0; n < 2; ++n) { const f32x4 g = acc[ai][0][m][n], gu = acc[ai][0][m][n] * acc[ai][1][m][n]; f32x4 r;
; #pragma unroll
;                     for (int e = 0; e < 4; ++e) r[e] = gu[e] * (s2 * __builtin_amdgcn_rcpf(1.f + __builtin_amdgcn_exp2f(cs * g[e])));
;                     o[n] = r; }
;                 *(u32x4*)(H + (size_t)row * ldc + (u.c0 >> 1) + wc * 32 + 8 * fq) = pack8(o[0], o[1]); }
	v_rcp_f32_e32 v86, v86
	v_rcp_f32_e32 v87, v87
	v_mad_i64_i32 v[172:173], s[30:31], v172, s64, v[170:171]
	v_lshl_add_u64 v[172:173], v[172:173], 0, s[2:3]
	v_lshl_add_u64 v[172:173], v[172:173], 0, s[8:9]
	v_lshl_add_u64 v[172:173], v[172:173], 0, v[136:137]
	v_pk_mul_f32 v[92:93], v[92:93], v[176:177] op_sel_hi:[1,0]
	v_pk_mul_f32 v[94:95], v[94:95], v[176:177] op_sel_hi:[1,0]
	v_pk_mul_f32 v[84:85], v[84:85], v[176:177] op_sel_hi:[1,0]
	v_pk_mul_f32 v[86:87], v[86:87], v[176:177] op_sel_hi:[1,0]
	v_pk_mul_f32 v[88:89], v[88:89], v[92:93]
	v_pk_mul_f32 v[90:91], v[90:91], v[94:95]
	v_pk_mul_f32 v[80:81], v[80:81], v[84:85]
	v_pk_mul_f32 v[82:83], v[82:83], v[86:87]
	v_cvt_pk_bf16_f32 v92, v88, v89
	v_cvt_pk_bf16_f32 v93, v90, v91
	v_cvt_pk_bf16_f32 v94, v80, v81
	v_cvt_pk_bf16_f32 v95, v82, v83
	flat_store_dwordx4 v[172:173], v[92:95]
	v_pk_mul_f32 v[72:73], v[76:77], v[72:73]
	v_pk_mul_f32 v[74:75], v[78:79], v[74:75]
	v_pk_mul_f32 v[64:65], v[68:69], v[64:65]
	v_pk_mul_f32 v[66:67], v[70:71], v[66:67]
	v_mul_f32_e32 v174, 0xbfb8aa3b, v187
	v_mul_f32_e32 v176, v187, v187
	v_pk_mul_f32 v[76:77], v[76:77], v[174:175] op_sel_hi:[1,0]
	v_pk_mul_f32 v[78:79], v[78:79], v[174:175] op_sel_hi:[1,0]
	v_pk_mul_f32 v[68:69], v[68:69], v[174:175] op_sel_hi:[1,0]
	v_pk_mul_f32 v[70:71], v[70:71], v[174:175] op_sel_hi:[1,0]
	v_exp_f32_e32 v76, v76
	v_exp_f32_e32 v77, v77
	v_exp_f32_e32 v78, v78
	v_exp_f32_e32 v79, v79
	v_exp_f32_e32 v68, v68
	v_exp_f32_e32 v69, v69
	v_exp_f32_e32 v70, v70
	v_exp_f32_e32 v71, v71
	v_pk_add_f32 v[76:77], v[76:77], v[180:181] op_sel_hi:[1,0]
	v_pk_add_f32 v[78:79], v[78:79], v[180:181] op_sel_hi:[1,0]
	v_pk_add_f32 v[68:69], v[68:69], v[180:181] op_sel_hi:[1,0]
	v_pk_add_f32 v[70:71], v[70:71], v[180:181] op_sel_hi:[1,0]
	v_add_u32_e32 v172, s60, v153
	v_rcp_f32_e32 v76, v76
	v_rcp_f32_e32 v77, v77
	v_rcp_f32_e32 v78, v78
	v_rcp_f32_e32 v79, v79
	v_rcp_f32_e32 v68, v68
	v_rcp_f32_e32 v69, v69
	v_rcp_f32_e32 v70, v70
	v_rcp_f32_e32 v71, v71
	v_mad_i64_i32 v[172:173], s[30:31], v172, s64, v[170:171]
	v_lshl_add_u64 v[172:173], v[172:173], 0, s[2:3]
	v_lshl_add_u64 v[172:173], v[172:173], 0, s[8:9]
	v_lshl_add_u64 v[172:173], v[172:173], 0, v[136:137]
	v_pk_mul_f32 v[76:77], v[76:77], v[176:177] op_sel_hi:[1,0]
	v_pk_mul_f32 v[78:79], v[78:79], v[176:177] op_sel_hi:[1,0]
	v_pk_mul_f32 v[68:69], v[68:69], v[176:177] op_sel_hi:[1,0]
	v_pk_mul_f32 v[70:71], v[70:71], v[176:177] op_sel_hi:[1,0]
	v_pk_mul_f32 v[72:73], v[72:73], v[76:77]
	v_pk_mul_f32 v[74:75], v[74:75], v[78:79]
	v_pk_mul_f32 v[64:65], v[64:65], v[68:69]
	v_pk_mul_f32 v[66:67], v[66:67], v[70:71]
	v_cvt_pk_bf16_f32 v76, v72, v73
	v_cvt_pk_bf16_f32 v77, v74, v75
	v_cvt_pk_bf16_f32 v78, v64, v65
	v_cvt_pk_bf16_f32 v79, v66, v67
	flat_store_dwordx4 v[172:173], v[76:79]
	v_pk_mul_f32 v[56:57], v[60:61], v[56:57]
	v_pk_mul_f32 v[58:59], v[62:63], v[58:59]
	v_pk_mul_f32 v[48:49], v[52:53], v[48:49]
	v_pk_mul_f32 v[50:51], v[54:55], v[50:51]
	v_mul_f32_e32 v174, 0xbfb8aa3b, v188
	v_mul_f32_e32 v176, v188, v188
	v_pk_mul_f32 v[60:61], v[60:61], v[174:175] op_sel_hi:[1,0]
	v_pk_mul_f32 v[62:63], v[62:63], v[174:175] op_sel_hi:[1,0]
	v_pk_mul_f32 v[52:53], v[52:53], v[174:175] op_sel_hi:[1,0]
	v_pk_mul_f32 v[54:55], v[54:55], v[174:175] op_sel_hi:[1,0]
	v_exp_f32_e32 v60, v60
	v_exp_f32_e32 v61, v61
	v_exp_f32_e32 v62, v62
	v_exp_f32_e32 v63, v63
	v_exp_f32_e32 v52, v52
	v_exp_f32_e32 v53, v53
	v_exp_f32_e32 v54, v54
	v_exp_f32_e32 v55, v55
	v_pk_add_f32 v[60:61], v[60:61], v[180:181] op_sel_hi:[1,0]
	v_pk_add_f32 v[62:63], v[62:63], v[180:181] op_sel_hi:[1,0]
	v_pk_add_f32 v[52:53], v[52:53], v[180:181] op_sel_hi:[1,0]
	v_pk_add_f32 v[54:55], v[54:55], v[180:181] op_sel_hi:[1,0]
	v_add_u32_e32 v172, s60, v156
	v_rcp_f32_e32 v60, v60
	v_rcp_f32_e32 v61, v61
	v_rcp_f32_e32 v62, v62
	v_rcp_f32_e32 v63, v63
	v_rcp_f32_e32 v52, v52
	v_rcp_f32_e32 v53, v53
	v_rcp_f32_e32 v54, v54
	v_rcp_f32_e32 v55, v55
	v_mad_i64_i32 v[172:173], s[30:31], v172, s64, v[170:171]
	v_lshl_add_u64 v[172:173], v[172:173], 0, s[2:3]
	v_lshl_add_u64 v[172:173], v[172:173], 0, s[8:9]
	v_lshl_add_u64 v[172:173], v[172:173], 0, v[136:137]
	v_pk_mul_f32 v[60:61], v[60:61], v[176:177] op_sel_hi:[1,0]
	v_pk_mul_f32 v[62:63], v[62:63], v[176:177] op_sel_hi:[1,0]
	v_pk_mul_f32 v[52:53], v[52:53], v[176:177] op_sel_hi:[1,0]
	v_pk_mul_f32 v[54:55], v[54:55], v[176:177] op_sel_hi:[1,0]
	v_pk_mul_f32 v[56:57], v[56:57], v[60:61]
	v_pk_mul_f32 v[58:59], v[58:59], v[62:63]
	v_pk_mul_f32 v[48:49], v[48:49], v[52:53]
	v_pk_mul_f32 v[50:51], v[50:51], v[54:55]
	v_cvt_pk_bf16_f32 v60, v56, v57
	v_cvt_pk_bf16_f32 v61, v58, v59
	v_cvt_pk_bf16_f32 v62, v48, v49
	v_cvt_pk_bf16_f32 v63, v50, v51
	flat_store_dwordx4 v[172:173], v[60:63]
	v_pk_mul_f32 v[40:41], v[44:45], v[40:41]
	v_pk_mul_f32 v[42:43], v[46:47], v[42:43]
	v_pk_mul_f32 v[32:33], v[36:37], v[32:33]
	v_pk_mul_f32 v[34:35], v[38:39], v[34:35]
	v_mul_f32_e32 v174, 0xbfb8aa3b, v189
	v_mul_f32_e32 v176, v189, v189
	v_pk_mul_f32 v[44:45], v[44:45], v[174:175] op_sel_hi:[1,0]
	v_pk_mul_f32 v[46:47], v[46:47], v[174:175] op_sel_hi:[1,0]
	v_pk_mul_f32 v[36:37], v[36:37], v[174:175] op_sel_hi:[1,0]
	v_pk_mul_f32 v[38:39], v[38:39], v[174:175] op_sel_hi:[1,0]
	v_exp_f32_e32 v44, v44
	v_exp_f32_e32 v45, v45
	v_exp_f32_e32 v46, v46
	v_exp_f32_e32 v47, v47
; __device__ __forceinline__ u32x4 pack8(f32x4 v0, f32x4 v1) { u32x4 w; w.x = cvt_pk_bf16(v0[0], v0[1]); w.y = cvt_pk_bf16(v0[2], v0[3]); w.z = cvt_pk_bf16(v1[0], v1[1]); w.w = cvt_pk_bf16(v1[2], v1[3]); return w; }
; #define PG8_BAR __builtin_amdgcn_s_barrier()
;     __device__ __forceinline__ void operator()(Acc& acc, const Unit& u, int wr, int wc, int fr, int fq, PG8_LAS unsigned char* xl) const {
;     ...
;             for (int m = 0; m < 4; ++m) { const int rl = ai * HALF + wr * 64 + m * 16 + fr; const int row = u.r0 + rl; const float s = S[rl], cs = -LOG2E * s, s2 = s * s;
;                 f32x4 o[2];
; #pragma unroll
;                 for (int n = 0; n < 2; ++n) { const f32x4 g = acc[ai][0][m][n], gu = acc[ai][0][m][n] * acc[ai][1][m][n]; f32x4 r;
; #pragma unroll
;                     for (int e = 0; e < 4; ++e) r[e] = gu[e] * (s2 * __builtin_amdgcn_rcpf(1.f + __builtin_amdgcn_exp2f(cs * g[e])));
;                     o[n] = r; }
;                 *(u32x4*)(H + (size_t)row * ldc + (u.c0 >> 1) + wc * 32 + 8 * fq) = pack8(o[0], o[1]); }
; template <class Epi, class Sched>
; __device__ __forceinline__ void gemm_phase(PG8_LAS unsigned char* lds, PG8_LAS unsigned char* xl, const Gemm g, const Sched& S, const Epi& E) {
;     ...
;         if (!has_next) break;
; #pragma unroll
;         for (int a = 0; a < 2; ++a)
; #pragma unroll
;             for (int b = 0; b < 2; ++b)
; #pragma unroll
;                 for (int m = 0; m < 4; ++m)
; #pragma unroll
;                     for (int n = 0; n < 2; ++n) acc[a][b][m][n] = (f32x4){0.f, 0.f, 0.f, 0.f};
;         cur = nxt; cA = nA; cB = nB; ++ui;
;         if (wr == 1) PG8_BAR;
	v_exp_f32_e32 v36, v36
	v_exp_f32_e32 v37, v37
	v_exp_f32_e32 v38, v38
	v_exp_f32_e32 v39, v39
	v_pk_add_f32 v[44:45], v[44:45], v[180:181] op_sel_hi:[1,0]
	v_pk_add_f32 v[46:47], v[46:47], v[180:181] op_sel_hi:[1,0]
	v_pk_add_f32 v[36:37], v[36:37], v[180:181] op_sel_hi:[1,0]
	v_pk_add_f32 v[38:39], v[38:39], v[180:181] op_sel_hi:[1,0]
	v_add_u32_e32 v172, s60, v158
	v_rcp_f32_e32 v44, v44
	v_rcp_f32_e32 v45, v45
	v_rcp_f32_e32 v46, v46
	v_rcp_f32_e32 v47, v47
	v_rcp_f32_e32 v36, v36
	v_rcp_f32_e32 v37, v37
	v_rcp_f32_e32 v38, v38
	v_rcp_f32_e32 v39, v39
	v_mad_i64_i32 v[172:173], s[30:31], v172, s64, v[170:171]
	v_lshl_add_u64 v[172:173], v[172:173], 0, s[2:3]
	v_lshl_add_u64 v[172:173], v[172:173], 0, s[8:9]
	v_lshl_add_u64 v[172:173], v[172:173], 0, v[136:137]
	v_pk_mul_f32 v[44:45], v[44:45], v[176:177] op_sel_hi:[1,0]
	v_pk_mul_f32 v[46:47], v[46:47], v[176:177] op_sel_hi:[1,0]
	v_pk_mul_f32 v[36:37], v[36:37], v[176:177] op_sel_hi:[1,0]
	v_pk_mul_f32 v[38:39], v[38:39], v[176:177] op_sel_hi:[1,0]
	v_pk_mul_f32 v[40:41], v[40:41], v[44:45]
	v_pk_mul_f32 v[42:43], v[42:43], v[46:47]
	v_pk_mul_f32 v[32:33], v[32:33], v[36:37]
	v_pk_mul_f32 v[34:35], v[34:35], v[38:39]
	v_cvt_pk_bf16_f32 v44, v40, v41
	v_cvt_pk_bf16_f32 v45, v42, v43
	v_cvt_pk_bf16_f32 v46, v32, v33
	v_cvt_pk_bf16_f32 v47, v34, v35
	flat_store_dwordx4 v[172:173], v[44:47]
	v_pk_mul_f32 v[24:25], v[28:29], v[24:25]
	v_pk_mul_f32 v[26:27], v[30:31], v[26:27]
	v_pk_mul_f32 v[16:17], v[20:21], v[16:17]
	v_pk_mul_f32 v[18:19], v[22:23], v[18:19]
	v_mul_f32_e32 v174, 0xbfb8aa3b, v190
	v_mul_f32_e32 v176, v190, v190
	v_pk_mul_f32 v[28:29], v[28:29], v[174:175] op_sel_hi:[1,0]
	v_pk_mul_f32 v[30:31], v[30:31], v[174:175] op_sel_hi:[1,0]
	v_pk_mul_f32 v[20:21], v[20:21], v[174:175] op_sel_hi:[1,0]
	v_pk_mul_f32 v[22:23], v[22:23], v[174:175] op_sel_hi:[1,0]
	v_exp_f32_e32 v28, v28
	v_exp_f32_e32 v29, v29
	v_exp_f32_e32 v30, v30
	v_exp_f32_e32 v31, v31
	v_exp_f32_e32 v20, v20
	v_exp_f32_e32 v21, v21
	v_exp_f32_e32 v22, v22
	v_exp_f32_e32 v23, v23
	v_pk_add_f32 v[28:29], v[28:29], v[180:181] op_sel_hi:[1,0]
	v_pk_add_f32 v[30:31], v[30:31], v[180:181] op_sel_hi:[1,0]
	v_pk_add_f32 v[20:21], v[20:21], v[180:181] op_sel_hi:[1,0]
	v_pk_add_f32 v[22:23], v[22:23], v[180:181] op_sel_hi:[1,0]
	v_add_u32_e32 v172, s60, v160
	v_rcp_f32_e32 v28, v28
	v_rcp_f32_e32 v29, v29
	v_rcp_f32_e32 v30, v30
	v_rcp_f32_e32 v31, v31
	v_rcp_f32_e32 v20, v20
	v_rcp_f32_e32 v21, v21
	v_rcp_f32_e32 v22, v22
	v_rcp_f32_e32 v23, v23
	v_mad_i64_i32 v[172:173], s[30:31], v172, s64, v[170:171]
	v_lshl_add_u64 v[172:173], v[172:173], 0, s[2:3]
	v_lshl_add_u64 v[172:173], v[172:173], 0, s[8:9]
	v_lshl_add_u64 v[172:173], v[172:173], 0, v[136:137]
	v_pk_mul_f32 v[28:29], v[28:29], v[176:177] op_sel_hi:[1,0]
	v_pk_mul_f32 v[30:31], v[30:31], v[176:177] op_sel_hi:[1,0]
	v_pk_mul_f32 v[20:21], v[20:21], v[176:177] op_sel_hi:[1,0]
	v_pk_mul_f32 v[22:23], v[22:23], v[176:177] op_sel_hi:[1,0]
	v_pk_mul_f32 v[24:25], v[24:25], v[28:29]
	v_pk_mul_f32 v[26:27], v[26:27], v[30:31]
	v_pk_mul_f32 v[16:17], v[16:17], v[20:21]
	v_pk_mul_f32 v[18:19], v[18:19], v[22:23]
	v_cvt_pk_bf16_f32 v28, v24, v25
	v_cvt_pk_bf16_f32 v29, v26, v27
	v_cvt_pk_bf16_f32 v30, v16, v17
	v_cvt_pk_bf16_f32 v31, v18, v19
	flat_store_dwordx4 v[172:173], v[28:31]
	v_pk_mul_f32 v[8:9], v[12:13], v[8:9]
	v_pk_mul_f32 v[10:11], v[14:15], v[10:11]
	v_pk_mul_f32 v[0:1], v[4:5], v[0:1]
	v_pk_mul_f32 v[2:3], v[6:7], v[2:3]
	v_mul_f32_e32 v174, 0xbfb8aa3b, v191
	v_mul_f32_e32 v176, v191, v191
	v_pk_mul_f32 v[12:13], v[12:13], v[174:175] op_sel_hi:[1,0]
	v_pk_mul_f32 v[14:15], v[14:15], v[174:175] op_sel_hi:[1,0]
	v_pk_mul_f32 v[4:5], v[4:5], v[174:175] op_sel_hi:[1,0]
	v_pk_mul_f32 v[6:7], v[6:7], v[174:175] op_sel_hi:[1,0]
	v_exp_f32_e32 v12, v12
	v_exp_f32_e32 v13, v13
	v_exp_f32_e32 v14, v14
	v_exp_f32_e32 v15, v15
	v_exp_f32_e32 v4, v4
	v_exp_f32_e32 v5, v5
	v_exp_f32_e32 v6, v6
	v_exp_f32_e32 v7, v7
	v_pk_add_f32 v[12:13], v[12:13], v[180:181] op_sel_hi:[1,0]
	v_pk_add_f32 v[14:15], v[14:15], v[180:181] op_sel_hi:[1,0]
	v_pk_add_f32 v[4:5], v[4:5], v[180:181] op_sel_hi:[1,0]
	v_pk_add_f32 v[6:7], v[6:7], v[180:181] op_sel_hi:[1,0]
	v_add_u32_e32 v172, s60, v162
	v_rcp_f32_e32 v12, v12
	v_rcp_f32_e32 v13, v13
	v_rcp_f32_e32 v14, v14
	v_rcp_f32_e32 v15, v15
	v_rcp_f32_e32 v4, v4
	v_rcp_f32_e32 v5, v5
	v_rcp_f32_e32 v6, v6
	v_rcp_f32_e32 v7, v7
	v_mad_i64_i32 v[172:173], s[30:31], v172, s64, v[170:171]
	v_lshl_add_u64 v[172:173], v[172:173], 0, s[2:3]
	v_lshl_add_u64 v[172:173], v[172:173], 0, s[8:9]
	v_lshl_add_u64 v[172:173], v[172:173], 0, v[136:137]
	v_pk_mul_f32 v[12:13], v[12:13], v[176:177] op_sel_hi:[1,0]
	v_pk_mul_f32 v[14:15], v[14:15], v[176:177] op_sel_hi:[1,0]
	v_pk_mul_f32 v[4:5], v[4:5], v[176:177] op_sel_hi:[1,0]
	v_pk_mul_f32 v[6:7], v[6:7], v[176:177] op_sel_hi:[1,0]
	v_pk_mul_f32 v[8:9], v[8:9], v[12:13]
	v_pk_mul_f32 v[10:11], v[10:11], v[14:15]
	v_pk_mul_f32 v[0:1], v[0:1], v[4:5]
	v_pk_mul_f32 v[2:3], v[2:3], v[6:7]
	v_cvt_pk_bf16_f32 v12, v8, v9
	v_cvt_pk_bf16_f32 v13, v10, v11
	v_cvt_pk_bf16_f32 v14, v0, v1
	v_cvt_pk_bf16_f32 v15, v2, v3
	flat_store_dwordx4 v[172:173], v[12:15]
	s_mov_b64 s[2:3], -1
	s_cbranch_vccnz .LBB0_821
	s_andn2_b64 vcc, exec, s[10:11]
	s_cbranch_vccnz .LBB0_820
	s_barrier
	s_branch .LBB0_820
